# v14 plus MLA loop barrier moved before the last 3 PV MFMAs (MFMA-first head after the barrier)
# speedup vs baseline: 1.0097x; 1.0009x over previous
; #define MFMA(a, b, c) __builtin_amdgcn_mfma_f32_32x32x16_bf16((a), (b), (c), 0, 0, 0)
; template <int DQK, bool ALIBI>
; DI void attn_pass(const u16* __restrict__ Qp, int ldq, const u16* __restrict__ Kp, int ldk, const u16* __restrict__ VTp,
;                   int seq_start, int kt_lo, int kt_hi, int q0, float slope2, f32x16 (&O)[4], float& lsum, char* lds) {
;     ...
; #pragma unroll
;     for (int s = 0; s < 2; ++s)
; #pragma unroll
;       for (int db = 0; db < 4; ++db) O[db] = MFMA(vg[s][db], pg[s], O[db]);
;     __syncthreads();
.Lmy_mla_pv1:
	s_waitcnt lgkmcnt(4)
	v_mfma_f32_32x32x16_bf16 v[50:65], v[162:165], v[66:69], v[50:65]
	s_add_i32 s49, s49, 1
	s_add_i32 s44, s48, s49
	s_add_i32 s68, s68, 64
	v_lshl_add_u64 v[144:145], v[144:145], 0, s[80:81]
	v_lshl_add_u64 v[146:147], v[146:147], 0, s[80:81]
	s_cmp_lg_u32 s44, 2
	s_waitcnt lgkmcnt(3)
	v_mfma_f32_32x32x16_bf16 v[34:49], v[86:89], v[66:69], v[34:49]
	v_mfma_f32_32x32x16_bf16 v[18:33], v[90:93], v[66:69], v[18:33]
	v_mfma_f32_32x32x16_bf16 v[2:17], v[94:97], v[66:69], v[2:17]
	v_mfma_f32_32x32x16_bf16 v[50:65], v[166:169], v[70:73], v[50:65]
	s_waitcnt lgkmcnt(0)
	s_barrier
	v_mfma_f32_32x32x16_bf16 v[34:49], v[170:173], v[70:73], v[34:49]
	v_mfma_f32_32x32x16_bf16 v[18:33], v[174:177], v[70:73], v[18:33]
	v_mfma_f32_32x32x16_bf16 v[2:17], v[82:85], v[70:73], v[2:17]
	s_cbranch_scc0 .LBB0_1170
	s_branch .LBB0_1193
